# EpiLat: the two per-row partial sums of squares written by one store (quarter-row 0/1 lanes) instead of two
# baseline (speedup 1.0000x reference)
.Llat_norope2:
	s_lshl_b32 s0, s28, 9
	s_lshl_b32 s24, s90, 1
	s_or_b32 s0, s0, s24
	v_lshl_or_b32 v130, v146, 3, s0
	v_mad_u32_u24 v130, v0, s46, v130
	s_lshl_b32 s0, s28, 5
	s_lshl_b32 s24, s88, 2
	s_or_b32 s0, s0, s24
	v_mov_b32_e32 v133, s0
	v_mad_u32_u24 v133, v0, s61, v133
	s_mov_b32 vcc_lo, 0xffff0000
	s_mov_b32 vcc_hi, 0xffff0000
	v_lshlrev_b32_e32 v131, 3, v146
	v_add_u32_e32 v130, v130, v131
	v_pk_mul_f32 v[142:143], v[126:127], v[126:127]
	v_pk_fma_f32 v[142:143], v[128:129], v[128:129], v[142:143]
	v_pk_fma_f32 v[142:143], v[122:123], v[122:123], v[142:143]
	v_pk_fma_f32 v[142:143], v[124:125], v[124:125], v[142:143]
	v_cvt_pk_bf16_f32 v126, v126, v127
	v_cvt_pk_bf16_f32 v127, v128, v129
	v_cvt_pk_bf16_f32 v122, v122, v123
	v_cvt_pk_bf16_f32 v123, v124, v125
	v_add_f32_e32 v150, v142, v143
	v_pk_mul_f32 v[148:149], v[118:119], v[118:119]
	v_pk_fma_f32 v[148:149], v[120:121], v[120:121], v[148:149]
	v_pk_fma_f32 v[148:149], v[114:115], v[114:115], v[148:149]
	v_pk_fma_f32 v[148:149], v[116:117], v[116:117], v[148:149]
	v_cvt_pk_bf16_f32 v118, v118, v119
	v_cvt_pk_bf16_f32 v119, v120, v121
	v_cvt_pk_bf16_f32 v114, v114, v115
	v_cvt_pk_bf16_f32 v115, v116, v117
	v_add_f32_e32 v151, v148, v149
	v_pk_mul_f32 v[142:143], v[110:111], v[110:111]
	v_pk_fma_f32 v[142:143], v[112:113], v[112:113], v[142:143]
	v_pk_fma_f32 v[142:143], v[106:107], v[106:107], v[142:143]
	v_pk_fma_f32 v[142:143], v[108:109], v[108:109], v[142:143]
	v_cvt_pk_bf16_f32 v110, v110, v111
	v_cvt_pk_bf16_f32 v111, v112, v113
	v_cvt_pk_bf16_f32 v106, v106, v107
	v_cvt_pk_bf16_f32 v107, v108, v109
	v_add_f32_e32 v152, v142, v143
	v_pk_mul_f32 v[148:149], v[102:103], v[102:103]
	v_pk_fma_f32 v[148:149], v[104:105], v[104:105], v[148:149]
	v_pk_fma_f32 v[148:149], v[98:99], v[98:99], v[148:149]
	v_pk_fma_f32 v[148:149], v[100:101], v[100:101], v[148:149]
	v_cvt_pk_bf16_f32 v102, v102, v103
	v_cvt_pk_bf16_f32 v103, v104, v105
	v_cvt_pk_bf16_f32 v98, v98, v99
	v_cvt_pk_bf16_f32 v99, v100, v101
	v_add_f32_e32 v153, v148, v149
	v_permlane32_swap_b32_e32 v126, v122
	v_permlane32_swap_b32_e32 v127, v123
	v_permlane32_swap_b32_e32 v118, v114
	v_permlane32_swap_b32_e32 v119, v115
	v_permlane32_swap_b32_e32 v110, v106
	v_permlane32_swap_b32_e32 v111, v107
	v_permlane32_swap_b32_e32 v102, v98
	v_permlane32_swap_b32_e32 v103, v99
	v_cndmask_b32_e32 v128, v122, v126, vcc
	v_cndmask_b32_e32 v129, v123, v127, vcc
	v_cndmask_b32_e32 v120, v114, v118, vcc
	v_cndmask_b32_e32 v121, v115, v119, vcc
	v_cndmask_b32_e32 v112, v106, v110, vcc
	v_cndmask_b32_e32 v113, v107, v111, vcc
	v_cndmask_b32_e32 v104, v98, v102, vcc
	v_cndmask_b32_e32 v105, v99, v103, vcc
	ds_swizzle_b32 v124, v128 offset:swizzle(SWAP,16)
	ds_swizzle_b32 v125, v129 offset:swizzle(SWAP,16)
	ds_swizzle_b32 v116, v120 offset:swizzle(SWAP,16)
	ds_swizzle_b32 v117, v121 offset:swizzle(SWAP,16)
	ds_swizzle_b32 v108, v112 offset:swizzle(SWAP,16)
	ds_swizzle_b32 v109, v113 offset:swizzle(SWAP,16)
	ds_swizzle_b32 v100, v104 offset:swizzle(SWAP,16)
	ds_swizzle_b32 v101, v105 offset:swizzle(SWAP,16)
	s_waitcnt lgkmcnt(0)
	v_add_u32_e32 v131, 0x0, v130
	v_cndmask_b32_e32 v126, v126, v124, vcc
	v_cndmask_b32_e32 v127, v127, v125, vcc
	v_cndmask_b32_e32 v128, v124, v122, vcc
	v_cndmask_b32_e32 v129, v125, v123, vcc
	global_store_dwordx4 v131, v[126:129], s[8:9]
	v_cndmask_b32_e32 v118, v118, v116, vcc
	v_cndmask_b32_e32 v119, v119, v117, vcc
	v_cndmask_b32_e32 v120, v116, v114, vcc
	v_cndmask_b32_e32 v121, v117, v115, vcc
	global_store_dwordx4 v131, v[118:121], s[8:9] offset:256
	v_add_u32_e32 v132, 0x6000, v130
	v_cndmask_b32_e32 v110, v110, v108, vcc
	v_cndmask_b32_e32 v111, v111, v109, vcc
	v_cndmask_b32_e32 v112, v108, v106, vcc
	v_cndmask_b32_e32 v113, v109, v107, vcc
	global_store_dwordx4 v132, v[110:113], s[8:9]
	v_cndmask_b32_e32 v102, v102, v100, vcc
	v_cndmask_b32_e32 v103, v103, v101, vcc
	v_cndmask_b32_e32 v104, v100, v98, vcc
	v_cndmask_b32_e32 v105, v101, v99, vcc
	global_store_dwordx4 v132, v[102:105], s[8:9] offset:256
	v_pk_mul_f32 v[142:143], v[94:95], v[94:95]
	v_pk_fma_f32 v[142:143], v[96:97], v[96:97], v[142:143]
	v_pk_fma_f32 v[142:143], v[90:91], v[90:91], v[142:143]
	v_pk_fma_f32 v[142:143], v[92:93], v[92:93], v[142:143]
	v_cvt_pk_bf16_f32 v94, v94, v95
	v_cvt_pk_bf16_f32 v95, v96, v97
	v_cvt_pk_bf16_f32 v90, v90, v91
	v_cvt_pk_bf16_f32 v91, v92, v93
	v_add_f32_e32 v154, v142, v143
	v_pk_mul_f32 v[148:149], v[86:87], v[86:87]
	v_pk_fma_f32 v[148:149], v[88:89], v[88:89], v[148:149]
	v_pk_fma_f32 v[148:149], v[82:83], v[82:83], v[148:149]
	v_pk_fma_f32 v[148:149], v[84:85], v[84:85], v[148:149]
	v_cvt_pk_bf16_f32 v86, v86, v87
	v_cvt_pk_bf16_f32 v87, v88, v89
	v_cvt_pk_bf16_f32 v82, v82, v83
	v_cvt_pk_bf16_f32 v83, v84, v85
	v_add_f32_e32 v155, v148, v149
	v_pk_mul_f32 v[142:143], v[78:79], v[78:79]
	v_pk_fma_f32 v[142:143], v[80:81], v[80:81], v[142:143]
	v_pk_fma_f32 v[142:143], v[74:75], v[74:75], v[142:143]
	v_pk_fma_f32 v[142:143], v[76:77], v[76:77], v[142:143]
	v_cvt_pk_bf16_f32 v78, v78, v79
	v_cvt_pk_bf16_f32 v79, v80, v81
	v_cvt_pk_bf16_f32 v74, v74, v75
	v_cvt_pk_bf16_f32 v75, v76, v77
	v_add_f32_e32 v156, v142, v143
	v_pk_mul_f32 v[148:149], v[70:71], v[70:71]
	v_pk_fma_f32 v[148:149], v[72:73], v[72:73], v[148:149]
	v_pk_fma_f32 v[148:149], v[66:67], v[66:67], v[148:149]
	v_pk_fma_f32 v[148:149], v[68:69], v[68:69], v[148:149]
	v_cvt_pk_bf16_f32 v70, v70, v71
	v_cvt_pk_bf16_f32 v71, v72, v73
	v_cvt_pk_bf16_f32 v66, v66, v67
	v_cvt_pk_bf16_f32 v67, v68, v69
	v_add_f32_e32 v157, v148, v149
	v_permlane32_swap_b32_e32 v94, v90
	v_permlane32_swap_b32_e32 v95, v91
	v_permlane32_swap_b32_e32 v86, v82
	v_permlane32_swap_b32_e32 v87, v83
	v_permlane32_swap_b32_e32 v78, v74
	v_permlane32_swap_b32_e32 v79, v75
	v_permlane32_swap_b32_e32 v70, v66
	v_permlane32_swap_b32_e32 v71, v67
	v_cndmask_b32_e32 v96, v90, v94, vcc
	v_cndmask_b32_e32 v97, v91, v95, vcc
	v_cndmask_b32_e32 v88, v82, v86, vcc
	v_cndmask_b32_e32 v89, v83, v87, vcc
	v_cndmask_b32_e32 v80, v74, v78, vcc
	v_cndmask_b32_e32 v81, v75, v79, vcc
	v_cndmask_b32_e32 v72, v66, v70, vcc
	v_cndmask_b32_e32 v73, v67, v71, vcc
	ds_swizzle_b32 v92, v96 offset:swizzle(SWAP,16)
	ds_swizzle_b32 v93, v97 offset:swizzle(SWAP,16)
	ds_swizzle_b32 v84, v88 offset:swizzle(SWAP,16)
	ds_swizzle_b32 v85, v89 offset:swizzle(SWAP,16)
	ds_swizzle_b32 v76, v80 offset:swizzle(SWAP,16)
	ds_swizzle_b32 v77, v81 offset:swizzle(SWAP,16)
	ds_swizzle_b32 v68, v72 offset:swizzle(SWAP,16)
	ds_swizzle_b32 v69, v73 offset:swizzle(SWAP,16)
	s_waitcnt lgkmcnt(0)
	v_add_u32_e32 v131, 0xc000, v130
	v_cndmask_b32_e32 v94, v94, v92, vcc
	v_cndmask_b32_e32 v95, v95, v93, vcc
	v_cndmask_b32_e32 v96, v92, v90, vcc
	v_cndmask_b32_e32 v97, v93, v91, vcc
	global_store_dwordx4 v131, v[94:97], s[8:9]
	v_cndmask_b32_e32 v86, v86, v84, vcc
	v_cndmask_b32_e32 v87, v87, v85, vcc
	v_cndmask_b32_e32 v88, v84, v82, vcc
	v_cndmask_b32_e32 v89, v85, v83, vcc
	global_store_dwordx4 v131, v[86:89], s[8:9] offset:256
	v_add_u32_e32 v132, 0x12000, v130
	v_cndmask_b32_e32 v78, v78, v76, vcc
	v_cndmask_b32_e32 v79, v79, v77, vcc
	v_cndmask_b32_e32 v80, v76, v74, vcc
	v_cndmask_b32_e32 v81, v77, v75, vcc
	global_store_dwordx4 v132, v[78:81], s[8:9]
	v_cndmask_b32_e32 v70, v70, v68, vcc
	v_cndmask_b32_e32 v71, v71, v69, vcc
	v_cndmask_b32_e32 v72, v68, v66, vcc
	v_cndmask_b32_e32 v73, v69, v67, vcc
	global_store_dwordx4 v132, v[70:73], s[8:9] offset:256
	v_pk_mul_f32 v[142:143], v[62:63], v[62:63]
	v_pk_fma_f32 v[142:143], v[64:65], v[64:65], v[142:143]
	v_pk_fma_f32 v[142:143], v[58:59], v[58:59], v[142:143]
	v_pk_fma_f32 v[142:143], v[60:61], v[60:61], v[142:143]
	v_cvt_pk_bf16_f32 v62, v62, v63
	v_cvt_pk_bf16_f32 v63, v64, v65
	v_cvt_pk_bf16_f32 v58, v58, v59
	v_cvt_pk_bf16_f32 v59, v60, v61
	v_add_f32_e32 v158, v142, v143
	v_pk_mul_f32 v[148:149], v[54:55], v[54:55]
	v_pk_fma_f32 v[148:149], v[56:57], v[56:57], v[148:149]
	v_pk_fma_f32 v[148:149], v[50:51], v[50:51], v[148:149]
	v_pk_fma_f32 v[148:149], v[52:53], v[52:53], v[148:149]
	v_cvt_pk_bf16_f32 v54, v54, v55
	v_cvt_pk_bf16_f32 v55, v56, v57
	v_cvt_pk_bf16_f32 v50, v50, v51
	v_cvt_pk_bf16_f32 v51, v52, v53
	v_add_f32_e32 v159, v148, v149
	v_pk_mul_f32 v[142:143], v[46:47], v[46:47]
	v_pk_fma_f32 v[142:143], v[48:49], v[48:49], v[142:143]
	v_pk_fma_f32 v[142:143], v[42:43], v[42:43], v[142:143]
	v_pk_fma_f32 v[142:143], v[44:45], v[44:45], v[142:143]
	v_cvt_pk_bf16_f32 v46, v46, v47
	v_cvt_pk_bf16_f32 v47, v48, v49
	v_cvt_pk_bf16_f32 v42, v42, v43
	v_cvt_pk_bf16_f32 v43, v44, v45
	v_add_f32_e32 v160, v142, v143
	v_pk_mul_f32 v[148:149], v[38:39], v[38:39]
	v_pk_fma_f32 v[148:149], v[40:41], v[40:41], v[148:149]
	v_pk_fma_f32 v[148:149], v[34:35], v[34:35], v[148:149]
	v_pk_fma_f32 v[148:149], v[36:37], v[36:37], v[148:149]
	v_cvt_pk_bf16_f32 v38, v38, v39
	v_cvt_pk_bf16_f32 v39, v40, v41
	v_cvt_pk_bf16_f32 v34, v34, v35
	v_cvt_pk_bf16_f32 v35, v36, v37
	v_add_f32_e32 v161, v148, v149
	v_permlane32_swap_b32_e32 v62, v58
	v_permlane32_swap_b32_e32 v63, v59
	v_permlane32_swap_b32_e32 v54, v50
	v_permlane32_swap_b32_e32 v55, v51
	v_permlane32_swap_b32_e32 v46, v42
	v_permlane32_swap_b32_e32 v47, v43
	v_permlane32_swap_b32_e32 v38, v34
	v_permlane32_swap_b32_e32 v39, v35
	v_cndmask_b32_e32 v64, v58, v62, vcc
	v_cndmask_b32_e32 v65, v59, v63, vcc
	v_cndmask_b32_e32 v56, v50, v54, vcc
	v_cndmask_b32_e32 v57, v51, v55, vcc
	v_cndmask_b32_e32 v48, v42, v46, vcc
	v_cndmask_b32_e32 v49, v43, v47, vcc
	v_cndmask_b32_e32 v40, v34, v38, vcc
	v_cndmask_b32_e32 v41, v35, v39, vcc
	ds_swizzle_b32 v60, v64 offset:swizzle(SWAP,16)
	ds_swizzle_b32 v61, v65 offset:swizzle(SWAP,16)
	ds_swizzle_b32 v52, v56 offset:swizzle(SWAP,16)
	ds_swizzle_b32 v53, v57 offset:swizzle(SWAP,16)
	ds_swizzle_b32 v44, v48 offset:swizzle(SWAP,16)
	ds_swizzle_b32 v45, v49 offset:swizzle(SWAP,16)
	ds_swizzle_b32 v36, v40 offset:swizzle(SWAP,16)
	ds_swizzle_b32 v37, v41 offset:swizzle(SWAP,16)
	s_waitcnt lgkmcnt(0)
	v_add_u32_e32 v131, 0x30000, v130
	v_cndmask_b32_e32 v62, v62, v60, vcc
	v_cndmask_b32_e32 v63, v63, v61, vcc
	v_cndmask_b32_e32 v64, v60, v58, vcc
	v_cndmask_b32_e32 v65, v61, v59, vcc
	global_store_dwordx4 v131, v[62:65], s[8:9]
	v_cndmask_b32_e32 v54, v54, v52, vcc
	v_cndmask_b32_e32 v55, v55, v53, vcc
	v_cndmask_b32_e32 v56, v52, v50, vcc
	v_cndmask_b32_e32 v57, v53, v51, vcc
	global_store_dwordx4 v131, v[54:57], s[8:9] offset:256
	v_add_u32_e32 v132, 0x36000, v130
	v_cndmask_b32_e32 v46, v46, v44, vcc
	v_cndmask_b32_e32 v47, v47, v45, vcc
	v_cndmask_b32_e32 v48, v44, v42, vcc
	v_cndmask_b32_e32 v49, v45, v43, vcc
	global_store_dwordx4 v132, v[46:49], s[8:9]
	v_cndmask_b32_e32 v38, v38, v36, vcc
	v_cndmask_b32_e32 v39, v39, v37, vcc
	v_cndmask_b32_e32 v40, v36, v34, vcc
	v_cndmask_b32_e32 v41, v37, v35, vcc
	global_store_dwordx4 v132, v[38:41], s[8:9] offset:256
	v_pk_mul_f32 v[142:143], v[30:31], v[30:31]
	v_pk_fma_f32 v[142:143], v[32:33], v[32:33], v[142:143]
	v_pk_fma_f32 v[142:143], v[26:27], v[26:27], v[142:143]
	v_pk_fma_f32 v[142:143], v[28:29], v[28:29], v[142:143]
	v_cvt_pk_bf16_f32 v30, v30, v31
	v_cvt_pk_bf16_f32 v31, v32, v33
	v_cvt_pk_bf16_f32 v26, v26, v27
	v_cvt_pk_bf16_f32 v27, v28, v29
	v_add_f32_e32 v162, v142, v143
	v_pk_mul_f32 v[148:149], v[22:23], v[22:23]
	v_pk_fma_f32 v[148:149], v[24:25], v[24:25], v[148:149]
	v_pk_fma_f32 v[148:149], v[18:19], v[18:19], v[148:149]
	v_pk_fma_f32 v[148:149], v[20:21], v[20:21], v[148:149]
	v_cvt_pk_bf16_f32 v22, v22, v23
	v_cvt_pk_bf16_f32 v23, v24, v25
	v_cvt_pk_bf16_f32 v18, v18, v19
	v_cvt_pk_bf16_f32 v19, v20, v21
	v_add_f32_e32 v163, v148, v149
	v_pk_mul_f32 v[142:143], v[14:15], v[14:15]
	v_pk_fma_f32 v[142:143], v[16:17], v[16:17], v[142:143]
	v_pk_fma_f32 v[142:143], v[10:11], v[10:11], v[142:143]
	v_pk_fma_f32 v[142:143], v[12:13], v[12:13], v[142:143]
	v_cvt_pk_bf16_f32 v14, v14, v15
	v_cvt_pk_bf16_f32 v15, v16, v17
	v_cvt_pk_bf16_f32 v10, v10, v11
	v_cvt_pk_bf16_f32 v11, v12, v13
	v_add_f32_e32 v164, v142, v143
	v_pk_mul_f32 v[148:149], v[6:7], v[6:7]
	v_pk_fma_f32 v[148:149], v[8:9], v[8:9], v[148:149]
	v_pk_fma_f32 v[148:149], v[2:3], v[2:3], v[148:149]
	v_pk_fma_f32 v[148:149], v[4:5], v[4:5], v[148:149]
	v_cvt_pk_bf16_f32 v6, v6, v7
	v_cvt_pk_bf16_f32 v7, v8, v9
	v_cvt_pk_bf16_f32 v2, v2, v3
	v_cvt_pk_bf16_f32 v3, v4, v5
	v_add_f32_e32 v165, v148, v149
	v_permlane32_swap_b32_e32 v30, v26
	v_permlane32_swap_b32_e32 v31, v27
	v_permlane32_swap_b32_e32 v22, v18
	v_permlane32_swap_b32_e32 v23, v19
	v_permlane32_swap_b32_e32 v14, v10
	v_permlane32_swap_b32_e32 v15, v11
	v_permlane32_swap_b32_e32 v6, v2
	v_permlane32_swap_b32_e32 v7, v3
	v_cndmask_b32_e32 v32, v26, v30, vcc
	v_cndmask_b32_e32 v33, v27, v31, vcc
	v_cndmask_b32_e32 v24, v18, v22, vcc
	v_cndmask_b32_e32 v25, v19, v23, vcc
	v_cndmask_b32_e32 v16, v10, v14, vcc
	v_cndmask_b32_e32 v17, v11, v15, vcc
	v_cndmask_b32_e32 v8, v2, v6, vcc
	v_cndmask_b32_e32 v9, v3, v7, vcc
	ds_swizzle_b32 v28, v32 offset:swizzle(SWAP,16)
	ds_swizzle_b32 v29, v33 offset:swizzle(SWAP,16)
	ds_swizzle_b32 v20, v24 offset:swizzle(SWAP,16)
	ds_swizzle_b32 v21, v25 offset:swizzle(SWAP,16)
	ds_swizzle_b32 v12, v16 offset:swizzle(SWAP,16)
	ds_swizzle_b32 v13, v17 offset:swizzle(SWAP,16)
	ds_swizzle_b32 v4, v8 offset:swizzle(SWAP,16)
	ds_swizzle_b32 v5, v9 offset:swizzle(SWAP,16)
	s_waitcnt lgkmcnt(0)
	v_add_u32_e32 v131, 0x3c000, v130
	v_cndmask_b32_e32 v30, v30, v28, vcc
	v_cndmask_b32_e32 v31, v31, v29, vcc
	v_cndmask_b32_e32 v32, v28, v26, vcc
	v_cndmask_b32_e32 v33, v29, v27, vcc
	global_store_dwordx4 v131, v[30:33], s[8:9]
	v_cndmask_b32_e32 v22, v22, v20, vcc
	v_cndmask_b32_e32 v23, v23, v21, vcc
	v_cndmask_b32_e32 v24, v20, v18, vcc
	v_cndmask_b32_e32 v25, v21, v19, vcc
	global_store_dwordx4 v131, v[22:25], s[8:9] offset:256
	v_add_u32_e32 v132, 0x42000, v130
	v_cndmask_b32_e32 v14, v14, v12, vcc
	v_cndmask_b32_e32 v15, v15, v13, vcc
	v_cndmask_b32_e32 v16, v12, v10, vcc
	v_cndmask_b32_e32 v17, v13, v11, vcc
	global_store_dwordx4 v132, v[14:17], s[8:9]
	v_cndmask_b32_e32 v6, v6, v4, vcc
	v_cndmask_b32_e32 v7, v7, v5, vcc
	v_cndmask_b32_e32 v8, v4, v2, vcc
	v_cndmask_b32_e32 v9, v5, v3, vcc
	global_store_dwordx4 v132, v[6:9], s[8:9] offset:256
	ds_swizzle_b32 v166, v150 offset:swizzle(SWAP,16)
	ds_swizzle_b32 v167, v151 offset:swizzle(SWAP,16)
	ds_swizzle_b32 v168, v152 offset:swizzle(SWAP,16)
	ds_swizzle_b32 v169, v153 offset:swizzle(SWAP,16)
	ds_swizzle_b32 v170, v154 offset:swizzle(SWAP,16)
	ds_swizzle_b32 v171, v155 offset:swizzle(SWAP,16)
	ds_swizzle_b32 v172, v156 offset:swizzle(SWAP,16)
	ds_swizzle_b32 v173, v157 offset:swizzle(SWAP,16)
	ds_swizzle_b32 v174, v158 offset:swizzle(SWAP,16)
	ds_swizzle_b32 v175, v159 offset:swizzle(SWAP,16)
	ds_swizzle_b32 v176, v160 offset:swizzle(SWAP,16)
	ds_swizzle_b32 v177, v161 offset:swizzle(SWAP,16)
	ds_swizzle_b32 v178, v162 offset:swizzle(SWAP,16)
	ds_swizzle_b32 v179, v163 offset:swizzle(SWAP,16)
	ds_swizzle_b32 v180, v164 offset:swizzle(SWAP,16)
	ds_swizzle_b32 v181, v165 offset:swizzle(SWAP,16)
	s_waitcnt lgkmcnt(0)
	v_add_f32_e32 v150, v150, v166
	v_add_f32_e32 v151, v151, v167
	v_add_f32_e32 v152, v152, v168
	v_add_f32_e32 v153, v153, v169
	v_add_f32_e32 v154, v154, v170
	v_add_f32_e32 v155, v155, v171
	v_add_f32_e32 v156, v156, v172
	v_add_f32_e32 v157, v157, v173
	v_add_f32_e32 v158, v158, v174
	v_add_f32_e32 v159, v159, v175
	v_add_f32_e32 v160, v160, v176
	v_add_f32_e32 v161, v161, v177
	v_add_f32_e32 v162, v162, v178
	v_add_f32_e32 v163, v163, v179
	v_add_f32_e32 v164, v164, v180
	v_add_f32_e32 v165, v165, v181
	v_mov_b32_e32 v182, v150
	v_mov_b32_e32 v183, v151
	v_mov_b32_e32 v184, v152
	v_mov_b32_e32 v185, v153
	v_mov_b32_e32 v186, v154
	v_mov_b32_e32 v187, v155
	v_mov_b32_e32 v188, v156
	v_mov_b32_e32 v189, v157
	v_mov_b32_e32 v228, v158
	v_mov_b32_e32 v229, v159
	v_mov_b32_e32 v230, v160
	v_mov_b32_e32 v231, v161
	v_mov_b32_e32 v232, v162
	v_mov_b32_e32 v233, v163
	v_mov_b32_e32 v234, v164
	v_mov_b32_e32 v235, v165
	v_permlane32_swap_b32_e32 v150, v182
	v_permlane32_swap_b32_e32 v151, v183
	v_permlane32_swap_b32_e32 v152, v184
	v_permlane32_swap_b32_e32 v153, v185
	v_permlane32_swap_b32_e32 v154, v186
	v_permlane32_swap_b32_e32 v155, v187
	v_permlane32_swap_b32_e32 v156, v188
	v_permlane32_swap_b32_e32 v157, v189
	v_permlane32_swap_b32_e32 v158, v228
	v_permlane32_swap_b32_e32 v159, v229
	v_permlane32_swap_b32_e32 v160, v230
	v_permlane32_swap_b32_e32 v161, v231
	v_permlane32_swap_b32_e32 v162, v232
	v_permlane32_swap_b32_e32 v163, v233
	v_permlane32_swap_b32_e32 v164, v234
	v_permlane32_swap_b32_e32 v165, v235
	v_add_f32_e32 v150, v150, v182
	v_add_f32_e32 v151, v151, v183
	v_add_f32_e32 v152, v152, v184
	v_add_f32_e32 v153, v153, v185
	v_add_f32_e32 v154, v154, v186
	v_add_f32_e32 v155, v155, v187
	v_add_f32_e32 v156, v156, v188
	v_add_f32_e32 v157, v157, v189
	v_add_f32_e32 v158, v158, v228
	v_add_f32_e32 v159, v159, v229
	v_add_f32_e32 v160, v160, v230
	v_add_f32_e32 v161, v161, v231
	v_add_f32_e32 v162, v162, v232
	v_add_f32_e32 v163, v163, v233
	v_add_f32_e32 v164, v164, v234
	v_add_f32_e32 v165, v165, v235
	v_and_b32_e32 v144, 1, v146
	v_lshl_add_u32 v133, v144, 4, v133
	v_cndmask_b32_e32 v150, v150, v151, vcc
	v_cndmask_b32_e32 v152, v152, v153, vcc
	v_cndmask_b32_e32 v154, v154, v155, vcc
	v_cndmask_b32_e32 v156, v156, v157, vcc
	v_cndmask_b32_e32 v158, v158, v159, vcc
	v_cndmask_b32_e32 v160, v160, v161, vcc
	v_cndmask_b32_e32 v162, v162, v163, vcc
	v_cndmask_b32_e32 v164, v164, v165, vcc
	s_mov_b64 exec, 0xffffffff
	v_add_u32_e32 v144, 0x0, v133
	global_store_dword v144, v150, s[10:11]
	v_add_u32_e32 v145, 0x600, v133
	global_store_dword v145, v152, s[10:11]
	v_add_u32_e32 v144, 0xc00, v133
	global_store_dword v144, v154, s[10:11]
	v_add_u32_e32 v145, 0x1200, v133
	global_store_dword v145, v156, s[10:11]
	v_add_u32_e32 v144, 0x3000, v133
	global_store_dword v144, v158, s[10:11]
	v_add_u32_e32 v145, 0x3600, v133
	global_store_dword v145, v160, s[10:11]
	v_add_u32_e32 v144, 0x3c00, v133
	global_store_dword v144, v162, s[10:11]
	v_add_u32_e32 v145, 0x4200, v133
	global_store_dword v145, v164, s[10:11]
	s_mov_b64 exec, -1
	v_mov_b64_e32 v[194:195], 0xc0
	v_mov_b64_e32 v[196:197], 0xbf
	v_mov_b64_e32 v[198:199], 0x180
	v_mov_b64_e32 v[200:201], 0x17f
	v_mov_b64_e32 v[202:203], 0x200
	v_mov_b64_e32 v[204:205], 0x1ff
	v_mov_b64_e32 v[206:207], 0x100
	v_mov_b64_e32 v[208:209], 0xff
	v_mov_b32_e32 v221, 0x3e38aa3b
	v_mov_b32_e32 v222, 0x7c
	v_mov_b32_e32 v223, 0x80
	v_mov_b32_e32 v224, 0x42800000
	s_andn2_b64 vcc, exec, s[36:37]
	s_mov_b64 s[24:25], -1
	s_cbranch_vccnz .LBB0_122
